# EPI1 epilogue: 8 rs loads hoisted to epilogue top with counted vmcnt(7) waits (on top of EPI2 hoist, gla counts, seq remap)
# speedup vs baseline: 1.0195x; 1.0195x over previous
; __device__ __forceinline__ unsigned pack2(float a, float b) { f32v2_t v = {a, b}; bf16v2_t r = __builtin_convertvector(v, bf16v2_t); return __builtin_bit_cast(unsigned, r); }
; template <int EPI, int N, int K>
; __device__ __forceinline__ void gemm_phase(const KP& p, int l, const bfr* A, const bfr* Bt) {
;     ...
;         for (int m = 0; m < 4; ++m) {
;           int row = erow + ai * HM + wr * 64 + m * 16 + fr;
;           const float r = rs[row];
;           const float nrl = -1.44269504f * r, r2 = r * r;
;           u32x4 pk;
; #pragma unroll
;           for (int bj = 0; bj < 2; ++bj)
; #pragma unroll
;             for (int jj = 0; jj < 2; ++jj) {
;               f32v2_t g2 = {acc[ai][bj][m][0][2 * jj], acc[ai][bj][m][0][2 * jj + 1]};
;               f32v2_t u2 = {acc[ai][bj][m][1][2 * jj], acc[ai][bj][m][1][2 * jj + 1]};
;               f32v2_t t2 = g2 * nrl;
;               f32v2_t e2 = {__builtin_amdgcn_exp2f(t2.x), __builtin_amdgcn_exp2f(t2.y)};
;               f32v2_t d2 = e2 + 1.0f;
;               f32v2_t rc = {__builtin_amdgcn_rcpf(d2.x), __builtin_amdgcn_rcpf(d2.y)};
;               f32v2_t o2 = (g2 * u2) * r2 * rc;
;               pk[bj * 2 + jj] = pack2(o2.x, o2.y);
;             }
;           *(u32x4*)(act + (size_t)row * DFF + (ecol >> 1) + wc * 32 + fq * 8) = pk;
.LBB0_235:
	v_add_u32_e32 v134, s76, v147
	v_ashrrev_i32_e32 v135, 31, v134
	v_lshl_add_u64 v[166:167], v[134:135], 2, s[46:47]
	global_load_dword v135, v[166:167], off
	global_load_dword v178, v[166:167], off offset:64
	global_load_dword v179, v[166:167], off offset:128
	global_load_dword v180, v[166:167], off offset:192
	global_load_dword v181, v[166:167], off offset:512
	global_load_dword v182, v[166:167], off offset:576
	global_load_dword v183, v[166:167], off offset:640
	global_load_dword v184, v[166:167], off offset:704
	v_pk_mul_f32 v[128:129], v[124:125], v[128:129]
	s_ashr_i32 s2, s78, 1
	v_pk_mul_f32 v[120:121], v[116:117], v[120:121]
	s_ashr_i32 s3, s2, 31
	v_lshl_add_u64 v[132:133], s[2:3], 1, v[130:131]
	s_movk_i32 s14, 0x1600
	v_pk_mul_f32 v[112:113], v[108:109], v[112:113]
	v_pk_mul_f32 v[104:105], v[100:101], v[104:105]
	v_pk_mul_f32 v[96:97], v[92:93], v[96:97]
	v_pk_mul_f32 v[88:89], v[84:85], v[88:89]
	v_pk_mul_f32 v[80:81], v[76:77], v[80:81]
	v_pk_mul_f32 v[72:73], v[68:69], v[72:73]
	v_pk_mul_f32 v[64:65], v[60:61], v[64:65]
	v_pk_mul_f32 v[56:57], v[52:53], v[56:57]
	v_pk_mul_f32 v[48:49], v[44:45], v[48:49]
	v_pk_mul_f32 v[40:41], v[36:37], v[40:41]
	v_pk_mul_f32 v[32:33], v[28:29], v[32:33]
	v_pk_mul_f32 v[24:25], v[20:21], v[24:25]
	v_pk_mul_f32 v[16:17], v[12:13], v[16:17]
	v_pk_mul_f32 v[8:9], v[4:5], v[8:9]
	s_and_b64 vcc, exec, s[50:51]
	s_mov_b32 s76, s74
	s_mov_b32 s78, s52
	s_waitcnt vmcnt(7)
	v_mul_f32_e32 v0, 0xbfb8aa3b, v135
	v_pk_mul_f32 v[168:169], v[122:123], v[0:1] op_sel_hi:[1,0]
	v_pk_mul_f32 v[124:125], v[124:125], v[0:1] op_sel_hi:[1,0]
	v_exp_f32_e32 v168, v168
	v_exp_f32_e32 v169, v169
	v_exp_f32_e32 v124, v124
	v_exp_f32_e32 v125, v125
	v_mul_f32_e32 v166, v135, v135
	v_pk_add_f32 v[168:169], v[168:169], 1.0 op_sel_hi:[1,0]
	v_pk_mul_f32 v[122:123], v[122:123], v[126:127]
	v_pk_add_f32 v[124:125], v[124:125], 1.0 op_sel_hi:[1,0]
	v_rcp_f32_e32 v168, v168
	v_rcp_f32_e32 v169, v169
	v_rcp_f32_e32 v124, v124
	v_rcp_f32_e32 v125, v125
	v_pk_mul_f32 v[122:123], v[122:123], v[166:167] op_sel_hi:[1,0]
	v_pk_mul_f32 v[126:127], v[128:129], v[166:167] op_sel_hi:[1,0]
	v_pk_mul_f32 v[122:123], v[122:123], v[168:169]
	v_pk_mul_f32 v[124:125], v[126:127], v[124:125]
	v_cvt_pk_bf16_f32 v122, v122, v123
	v_cvt_pk_bf16_f32 v123, v124, v125
	v_pk_mul_f32 v[124:125], v[114:115], v[0:1] op_sel_hi:[1,0]
	v_pk_mul_f32 v[114:115], v[114:115], v[118:119]
	v_exp_f32_e32 v124, v124
	v_exp_f32_e32 v125, v125
	v_pk_mul_f32 v[114:115], v[114:115], v[166:167] op_sel_hi:[1,0]
	v_pk_add_f32 v[124:125], v[124:125], 1.0 op_sel_hi:[1,0]
	s_nop 0
	v_rcp_f32_e32 v124, v124
	v_rcp_f32_e32 v125, v125
	s_nop 0
	v_pk_mul_f32 v[114:115], v[114:115], v[124:125]
	s_nop 0
	v_cvt_pk_bf16_f32 v124, v114, v115
	v_pk_mul_f32 v[114:115], v[116:117], v[0:1] op_sel_hi:[1,0]
	v_pk_mul_f32 v[116:117], v[120:121], v[166:167] op_sel_hi:[1,0]
	v_exp_f32_e32 v114, v114
	v_exp_f32_e32 v115, v115
	s_nop 0
	v_pk_add_f32 v[114:115], v[114:115], 1.0 op_sel_hi:[1,0]
	s_nop 0
	v_rcp_f32_e32 v114, v114
	v_rcp_f32_e32 v115, v115
	s_nop 0
	v_pk_mul_f32 v[114:115], v[116:117], v[114:115]
	s_nop 0
	v_cvt_pk_bf16_f32 v125, v114, v115
	v_mad_i64_i32 v[114:115], s[2:3], v134, s14, v[132:133]
	global_store_dwordx4 v[114:115], v[122:125], off
	v_or_b32_e32 v114, 16, v134
	v_ashrrev_i32_e32 v115, 31, v114
	v_lshl_add_u64 v[116:117], v[114:115], 2, s[46:47]
	s_waitcnt vmcnt(7)
	v_mov_b32_e32 v115, v178
	v_mul_f32_e32 v0, 0xbfb8aa3b, v115
	v_pk_mul_f32 v[118:119], v[106:107], v[0:1] op_sel_hi:[1,0]
	v_pk_mul_f32 v[108:109], v[108:109], v[0:1] op_sel_hi:[1,0]
	v_exp_f32_e32 v118, v118
	v_exp_f32_e32 v119, v119
	v_exp_f32_e32 v108, v108
	v_exp_f32_e32 v109, v109
	v_mul_f32_e32 v116, v115, v115
	v_pk_add_f32 v[118:119], v[118:119], 1.0 op_sel_hi:[1,0]
	v_pk_mul_f32 v[106:107], v[106:107], v[110:111]
	v_pk_add_f32 v[108:109], v[108:109], 1.0 op_sel_hi:[1,0]
	v_rcp_f32_e32 v118, v118
	v_rcp_f32_e32 v119, v119
	v_rcp_f32_e32 v108, v108
	v_rcp_f32_e32 v109, v109
	v_pk_mul_f32 v[106:107], v[106:107], v[116:117] op_sel_hi:[1,0]
	v_pk_mul_f32 v[110:111], v[112:113], v[116:117] op_sel_hi:[1,0]
	v_pk_mul_f32 v[106:107], v[106:107], v[118:119]
	v_pk_mul_f32 v[108:109], v[110:111], v[108:109]
	v_cvt_pk_bf16_f32 v106, v106, v107
	v_cvt_pk_bf16_f32 v107, v108, v109
	v_pk_mul_f32 v[108:109], v[98:99], v[0:1] op_sel_hi:[1,0]
	v_pk_mul_f32 v[98:99], v[98:99], v[102:103]
	v_exp_f32_e32 v108, v108
	v_exp_f32_e32 v109, v109
	v_pk_mul_f32 v[98:99], v[98:99], v[116:117] op_sel_hi:[1,0]
	v_pk_add_f32 v[108:109], v[108:109], 1.0 op_sel_hi:[1,0]
	s_nop 0
	v_rcp_f32_e32 v108, v108
	v_rcp_f32_e32 v109, v109
	s_nop 0
	v_pk_mul_f32 v[98:99], v[98:99], v[108:109]
	s_nop 0
	v_cvt_pk_bf16_f32 v108, v98, v99
	v_pk_mul_f32 v[98:99], v[100:101], v[0:1] op_sel_hi:[1,0]
	v_pk_mul_f32 v[100:101], v[104:105], v[116:117] op_sel_hi:[1,0]
	v_exp_f32_e32 v98, v98
	v_exp_f32_e32 v99, v99
	s_nop 0
	v_pk_add_f32 v[98:99], v[98:99], 1.0 op_sel_hi:[1,0]
	s_nop 0
	v_rcp_f32_e32 v98, v98
	v_rcp_f32_e32 v99, v99
	s_nop 0
	v_pk_mul_f32 v[98:99], v[100:101], v[98:99]
	s_nop 0
	v_cvt_pk_bf16_f32 v109, v98, v99
	v_mad_i64_i32 v[98:99], s[2:3], v114, s14, v[132:133]
	global_store_dwordx4 v[98:99], v[106:109], off
	v_or_b32_e32 v98, 32, v134
	v_ashrrev_i32_e32 v99, 31, v98
	v_lshl_add_u64 v[100:101], v[98:99], 2, s[46:47]
	s_waitcnt vmcnt(7)
; __device__ __forceinline__ unsigned pack2(float a, float b) { f32v2_t v = {a, b}; bf16v2_t r = __builtin_convertvector(v, bf16v2_t); return __builtin_bit_cast(unsigned, r); }
; template <int EPI, int N, int K>
; __device__ __forceinline__ void gemm_phase(const KP& p, int l, const bfr* A, const bfr* Bt) {
;     ...
;         for (int m = 0; m < 4; ++m) {
;           int row = erow + ai * HM + wr * 64 + m * 16 + fr;
;           const float r = rs[row];
;           const float nrl = -1.44269504f * r, r2 = r * r;
;           u32x4 pk;
; #pragma unroll
;           for (int bj = 0; bj < 2; ++bj)
; #pragma unroll
;             for (int jj = 0; jj < 2; ++jj) {
;               f32v2_t g2 = {acc[ai][bj][m][0][2 * jj], acc[ai][bj][m][0][2 * jj + 1]};
;               f32v2_t u2 = {acc[ai][bj][m][1][2 * jj], acc[ai][bj][m][1][2 * jj + 1]};
;               f32v2_t t2 = g2 * nrl;
;               f32v2_t e2 = {__builtin_amdgcn_exp2f(t2.x), __builtin_amdgcn_exp2f(t2.y)};
;               f32v2_t d2 = e2 + 1.0f;
;               f32v2_t rc = {__builtin_amdgcn_rcpf(d2.x), __builtin_amdgcn_rcpf(d2.y)};
;               f32v2_t o2 = (g2 * u2) * r2 * rc;
;               pk[bj * 2 + jj] = pack2(o2.x, o2.y);
;             }
;           *(u32x4*)(act + (size_t)row * DFF + (ecol >> 1) + wc * 32 + fq * 8) = pk;
	v_mov_b32_e32 v99, v179
	v_mul_f32_e32 v0, 0xbfb8aa3b, v99
	v_pk_mul_f32 v[102:103], v[90:91], v[0:1] op_sel_hi:[1,0]
	v_pk_mul_f32 v[92:93], v[92:93], v[0:1] op_sel_hi:[1,0]
	v_exp_f32_e32 v102, v102
	v_exp_f32_e32 v103, v103
	v_exp_f32_e32 v92, v92
	v_exp_f32_e32 v93, v93
	v_mul_f32_e32 v100, v99, v99
	v_pk_add_f32 v[102:103], v[102:103], 1.0 op_sel_hi:[1,0]
	v_pk_mul_f32 v[90:91], v[90:91], v[94:95]
	v_pk_add_f32 v[92:93], v[92:93], 1.0 op_sel_hi:[1,0]
	v_rcp_f32_e32 v102, v102
	v_rcp_f32_e32 v103, v103
	v_rcp_f32_e32 v92, v92
	v_rcp_f32_e32 v93, v93
	v_pk_mul_f32 v[90:91], v[90:91], v[100:101] op_sel_hi:[1,0]
	v_pk_mul_f32 v[94:95], v[96:97], v[100:101] op_sel_hi:[1,0]
	v_pk_mul_f32 v[90:91], v[90:91], v[102:103]
	v_pk_mul_f32 v[92:93], v[94:95], v[92:93]
	v_cvt_pk_bf16_f32 v90, v90, v91
	v_cvt_pk_bf16_f32 v91, v92, v93
	v_pk_mul_f32 v[92:93], v[82:83], v[0:1] op_sel_hi:[1,0]
	v_pk_mul_f32 v[82:83], v[82:83], v[86:87]
	v_exp_f32_e32 v92, v92
	v_exp_f32_e32 v93, v93
	v_pk_mul_f32 v[82:83], v[82:83], v[100:101] op_sel_hi:[1,0]
	v_pk_add_f32 v[92:93], v[92:93], 1.0 op_sel_hi:[1,0]
	s_nop 0
	v_rcp_f32_e32 v92, v92
	v_rcp_f32_e32 v93, v93
	s_nop 0
	v_pk_mul_f32 v[82:83], v[82:83], v[92:93]
	s_nop 0
	v_cvt_pk_bf16_f32 v92, v82, v83
	v_pk_mul_f32 v[82:83], v[84:85], v[0:1] op_sel_hi:[1,0]
	v_pk_mul_f32 v[84:85], v[88:89], v[100:101] op_sel_hi:[1,0]
	v_exp_f32_e32 v82, v82
	v_exp_f32_e32 v83, v83
	s_nop 0
	v_pk_add_f32 v[82:83], v[82:83], 1.0 op_sel_hi:[1,0]
	s_nop 0
	v_rcp_f32_e32 v82, v82
	v_rcp_f32_e32 v83, v83
	s_nop 0
	v_pk_mul_f32 v[82:83], v[84:85], v[82:83]
	s_nop 0
	v_cvt_pk_bf16_f32 v93, v82, v83
	v_mad_i64_i32 v[82:83], s[2:3], v98, s14, v[132:133]
	global_store_dwordx4 v[82:83], v[90:93], off
	v_or_b32_e32 v82, 48, v134
	v_ashrrev_i32_e32 v83, 31, v82
	v_lshl_add_u64 v[84:85], v[82:83], 2, s[46:47]
	s_waitcnt vmcnt(7)
	v_mov_b32_e32 v83, v180
	v_mul_f32_e32 v0, 0xbfb8aa3b, v83
	v_pk_mul_f32 v[86:87], v[74:75], v[0:1] op_sel_hi:[1,0]
	v_pk_mul_f32 v[76:77], v[76:77], v[0:1] op_sel_hi:[1,0]
	v_exp_f32_e32 v86, v86
	v_exp_f32_e32 v87, v87
	v_exp_f32_e32 v76, v76
	v_exp_f32_e32 v77, v77
	v_mul_f32_e32 v84, v83, v83
	v_pk_add_f32 v[86:87], v[86:87], 1.0 op_sel_hi:[1,0]
	v_pk_mul_f32 v[74:75], v[74:75], v[78:79]
	v_pk_add_f32 v[76:77], v[76:77], 1.0 op_sel_hi:[1,0]
	v_rcp_f32_e32 v86, v86
	v_rcp_f32_e32 v87, v87
	v_rcp_f32_e32 v76, v76
	v_rcp_f32_e32 v77, v77
	v_pk_mul_f32 v[74:75], v[74:75], v[84:85] op_sel_hi:[1,0]
	v_pk_mul_f32 v[78:79], v[80:81], v[84:85] op_sel_hi:[1,0]
	v_pk_mul_f32 v[74:75], v[74:75], v[86:87]
	v_pk_mul_f32 v[76:77], v[78:79], v[76:77]
	v_cvt_pk_bf16_f32 v74, v74, v75
	v_cvt_pk_bf16_f32 v75, v76, v77
	v_pk_mul_f32 v[76:77], v[66:67], v[0:1] op_sel_hi:[1,0]
	v_pk_mul_f32 v[66:67], v[66:67], v[70:71]
	v_exp_f32_e32 v76, v76
	v_exp_f32_e32 v77, v77
	v_pk_mul_f32 v[66:67], v[66:67], v[84:85] op_sel_hi:[1,0]
	v_pk_add_f32 v[76:77], v[76:77], 1.0 op_sel_hi:[1,0]
	s_nop 0
	v_rcp_f32_e32 v76, v76
	v_rcp_f32_e32 v77, v77
	s_nop 0
	v_pk_mul_f32 v[66:67], v[66:67], v[76:77]
	s_nop 0
	v_cvt_pk_bf16_f32 v76, v66, v67
	v_pk_mul_f32 v[66:67], v[68:69], v[0:1] op_sel_hi:[1,0]
	v_pk_mul_f32 v[68:69], v[72:73], v[84:85] op_sel_hi:[1,0]
	v_exp_f32_e32 v66, v66
	v_exp_f32_e32 v67, v67
	s_nop 0
	v_pk_add_f32 v[66:67], v[66:67], 1.0 op_sel_hi:[1,0]
	s_nop 0
	v_rcp_f32_e32 v66, v66
	v_rcp_f32_e32 v67, v67
	s_nop 0
	v_pk_mul_f32 v[66:67], v[68:69], v[66:67]
	s_nop 0
	v_cvt_pk_bf16_f32 v77, v66, v67
	v_mad_i64_i32 v[66:67], s[2:3], v82, s14, v[132:133]
	global_store_dwordx4 v[66:67], v[74:77], off
	v_add_u32_e32 v66, 0x80, v134
	v_ashrrev_i32_e32 v67, 31, v66
	v_lshl_add_u64 v[68:69], v[66:67], 2, s[46:47]
	s_waitcnt vmcnt(7)
	v_mov_b32_e32 v67, v181
	v_mul_f32_e32 v0, 0xbfb8aa3b, v67
	v_pk_mul_f32 v[70:71], v[58:59], v[0:1] op_sel_hi:[1,0]
	v_pk_mul_f32 v[60:61], v[60:61], v[0:1] op_sel_hi:[1,0]
	v_exp_f32_e32 v70, v70
	v_exp_f32_e32 v71, v71
	v_exp_f32_e32 v60, v60
	v_exp_f32_e32 v61, v61
	v_mul_f32_e32 v68, v67, v67
	v_pk_add_f32 v[70:71], v[70:71], 1.0 op_sel_hi:[1,0]
	v_pk_mul_f32 v[58:59], v[58:59], v[62:63]
	v_pk_add_f32 v[60:61], v[60:61], 1.0 op_sel_hi:[1,0]
	v_rcp_f32_e32 v70, v70
	v_rcp_f32_e32 v71, v71
	v_rcp_f32_e32 v60, v60
	v_rcp_f32_e32 v61, v61
	v_pk_mul_f32 v[58:59], v[58:59], v[68:69] op_sel_hi:[1,0]
	v_pk_mul_f32 v[62:63], v[64:65], v[68:69] op_sel_hi:[1,0]
	v_pk_mul_f32 v[58:59], v[58:59], v[70:71]
	v_pk_mul_f32 v[60:61], v[62:63], v[60:61]
	v_cvt_pk_bf16_f32 v58, v58, v59
	v_cvt_pk_bf16_f32 v59, v60, v61
	v_pk_mul_f32 v[60:61], v[50:51], v[0:1] op_sel_hi:[1,0]
	v_pk_mul_f32 v[50:51], v[50:51], v[54:55]
	v_exp_f32_e32 v60, v60
	v_exp_f32_e32 v61, v61
	v_pk_mul_f32 v[50:51], v[50:51], v[68:69] op_sel_hi:[1,0]
	v_pk_add_f32 v[60:61], v[60:61], 1.0 op_sel_hi:[1,0]
	s_nop 0
	v_rcp_f32_e32 v60, v60
	v_rcp_f32_e32 v61, v61
	s_nop 0
	v_pk_mul_f32 v[50:51], v[50:51], v[60:61]
	s_nop 0
	v_cvt_pk_bf16_f32 v60, v50, v51
	v_pk_mul_f32 v[50:51], v[52:53], v[0:1] op_sel_hi:[1,0]
	v_pk_mul_f32 v[52:53], v[56:57], v[68:69] op_sel_hi:[1,0]
	v_exp_f32_e32 v50, v50
	v_exp_f32_e32 v51, v51
	s_nop 0
	v_pk_add_f32 v[50:51], v[50:51], 1.0 op_sel_hi:[1,0]
	s_nop 0
	v_rcp_f32_e32 v50, v50
	v_rcp_f32_e32 v51, v51
	s_nop 0
	v_pk_mul_f32 v[50:51], v[52:53], v[50:51]
	s_nop 0
	v_cvt_pk_bf16_f32 v61, v50, v51
	v_mad_i64_i32 v[50:51], s[2:3], v66, s14, v[132:133]
	global_store_dwordx4 v[50:51], v[58:61], off
	v_add_u32_e32 v50, 0x90, v134
	v_ashrrev_i32_e32 v51, 31, v50
	v_lshl_add_u64 v[52:53], v[50:51], 2, s[46:47]
	s_waitcnt vmcnt(7)
; __device__ __forceinline__ unsigned pack2(float a, float b) { f32v2_t v = {a, b}; bf16v2_t r = __builtin_convertvector(v, bf16v2_t); return __builtin_bit_cast(unsigned, r); }
; template <int EPI, int N, int K>
; __device__ __forceinline__ void gemm_phase(const KP& p, int l, const bfr* A, const bfr* Bt) {
;     ...
;         for (int m = 0; m < 4; ++m) {
;           int row = erow + ai * HM + wr * 64 + m * 16 + fr;
;           const float r = rs[row];
;           const float nrl = -1.44269504f * r, r2 = r * r;
;           u32x4 pk;
; #pragma unroll
;           for (int bj = 0; bj < 2; ++bj)
; #pragma unroll
;             for (int jj = 0; jj < 2; ++jj) {
;               f32v2_t g2 = {acc[ai][bj][m][0][2 * jj], acc[ai][bj][m][0][2 * jj + 1]};
;               f32v2_t u2 = {acc[ai][bj][m][1][2 * jj], acc[ai][bj][m][1][2 * jj + 1]};
;               f32v2_t t2 = g2 * nrl;
;               f32v2_t e2 = {__builtin_amdgcn_exp2f(t2.x), __builtin_amdgcn_exp2f(t2.y)};
;               f32v2_t d2 = e2 + 1.0f;
;               f32v2_t rc = {__builtin_amdgcn_rcpf(d2.x), __builtin_amdgcn_rcpf(d2.y)};
;               f32v2_t o2 = (g2 * u2) * r2 * rc;
;               pk[bj * 2 + jj] = pack2(o2.x, o2.y);
;             }
;           *(u32x4*)(act + (size_t)row * DFF + (ecol >> 1) + wc * 32 + fq * 8) = pk;
	v_mov_b32_e32 v51, v182
	v_mul_f32_e32 v0, 0xbfb8aa3b, v51
	v_pk_mul_f32 v[54:55], v[42:43], v[0:1] op_sel_hi:[1,0]
	v_pk_mul_f32 v[44:45], v[44:45], v[0:1] op_sel_hi:[1,0]
	v_exp_f32_e32 v54, v54
	v_exp_f32_e32 v55, v55
	v_exp_f32_e32 v44, v44
	v_exp_f32_e32 v45, v45
	v_mul_f32_e32 v52, v51, v51
	v_pk_add_f32 v[54:55], v[54:55], 1.0 op_sel_hi:[1,0]
	v_pk_mul_f32 v[42:43], v[42:43], v[46:47]
	v_pk_add_f32 v[44:45], v[44:45], 1.0 op_sel_hi:[1,0]
	v_rcp_f32_e32 v54, v54
	v_rcp_f32_e32 v55, v55
	v_rcp_f32_e32 v44, v44
	v_rcp_f32_e32 v45, v45
	v_pk_mul_f32 v[42:43], v[42:43], v[52:53] op_sel_hi:[1,0]
	v_pk_mul_f32 v[46:47], v[48:49], v[52:53] op_sel_hi:[1,0]
	v_pk_mul_f32 v[42:43], v[42:43], v[54:55]
	v_pk_mul_f32 v[44:45], v[46:47], v[44:45]
	v_cvt_pk_bf16_f32 v42, v42, v43
	v_cvt_pk_bf16_f32 v43, v44, v45
	v_pk_mul_f32 v[44:45], v[34:35], v[0:1] op_sel_hi:[1,0]
	v_pk_mul_f32 v[34:35], v[34:35], v[38:39]
	v_exp_f32_e32 v44, v44
	v_exp_f32_e32 v45, v45
	v_pk_mul_f32 v[34:35], v[34:35], v[52:53] op_sel_hi:[1,0]
	v_pk_add_f32 v[44:45], v[44:45], 1.0 op_sel_hi:[1,0]
	s_nop 0
	v_rcp_f32_e32 v44, v44
	v_rcp_f32_e32 v45, v45
	s_nop 0
	v_pk_mul_f32 v[34:35], v[34:35], v[44:45]
	s_nop 0
	v_cvt_pk_bf16_f32 v44, v34, v35
	v_pk_mul_f32 v[34:35], v[36:37], v[0:1] op_sel_hi:[1,0]
	v_pk_mul_f32 v[36:37], v[40:41], v[52:53] op_sel_hi:[1,0]
	v_exp_f32_e32 v34, v34
	v_exp_f32_e32 v35, v35
	s_nop 0
	v_pk_add_f32 v[34:35], v[34:35], 1.0 op_sel_hi:[1,0]
	s_nop 0
	v_rcp_f32_e32 v34, v34
	v_rcp_f32_e32 v35, v35
	s_nop 0
	v_pk_mul_f32 v[34:35], v[36:37], v[34:35]
	s_nop 0
	v_cvt_pk_bf16_f32 v45, v34, v35
	v_mad_i64_i32 v[34:35], s[2:3], v50, s14, v[132:133]
	global_store_dwordx4 v[34:35], v[42:45], off
	v_add_u32_e32 v34, 0xa0, v134
	v_ashrrev_i32_e32 v35, 31, v34
	v_lshl_add_u64 v[36:37], v[34:35], 2, s[46:47]
	s_waitcnt vmcnt(7)
	v_mov_b32_e32 v35, v183
	v_mul_f32_e32 v0, 0xbfb8aa3b, v35
	v_pk_mul_f32 v[38:39], v[26:27], v[0:1] op_sel_hi:[1,0]
	v_pk_mul_f32 v[28:29], v[28:29], v[0:1] op_sel_hi:[1,0]
	v_exp_f32_e32 v38, v38
	v_exp_f32_e32 v39, v39
	v_exp_f32_e32 v28, v28
	v_exp_f32_e32 v29, v29
	v_mul_f32_e32 v36, v35, v35
	v_pk_add_f32 v[38:39], v[38:39], 1.0 op_sel_hi:[1,0]
	v_pk_mul_f32 v[26:27], v[26:27], v[30:31]
	v_pk_add_f32 v[28:29], v[28:29], 1.0 op_sel_hi:[1,0]
	v_rcp_f32_e32 v38, v38
	v_rcp_f32_e32 v39, v39
	v_rcp_f32_e32 v28, v28
	v_rcp_f32_e32 v29, v29
	v_pk_mul_f32 v[26:27], v[26:27], v[36:37] op_sel_hi:[1,0]
	v_pk_mul_f32 v[30:31], v[32:33], v[36:37] op_sel_hi:[1,0]
	v_pk_mul_f32 v[26:27], v[26:27], v[38:39]
	v_pk_mul_f32 v[28:29], v[30:31], v[28:29]
	v_cvt_pk_bf16_f32 v26, v26, v27
	v_cvt_pk_bf16_f32 v27, v28, v29
	v_pk_mul_f32 v[28:29], v[18:19], v[0:1] op_sel_hi:[1,0]
	v_pk_mul_f32 v[18:19], v[18:19], v[22:23]
	v_exp_f32_e32 v28, v28
	v_exp_f32_e32 v29, v29
	v_pk_mul_f32 v[18:19], v[18:19], v[36:37] op_sel_hi:[1,0]
	v_pk_add_f32 v[28:29], v[28:29], 1.0 op_sel_hi:[1,0]
	s_nop 0
	v_rcp_f32_e32 v28, v28
	v_rcp_f32_e32 v29, v29
	s_nop 0
	v_pk_mul_f32 v[18:19], v[18:19], v[28:29]
	s_nop 0
	v_cvt_pk_bf16_f32 v28, v18, v19
	v_pk_mul_f32 v[18:19], v[20:21], v[0:1] op_sel_hi:[1,0]
	v_pk_mul_f32 v[20:21], v[24:25], v[36:37] op_sel_hi:[1,0]
	v_exp_f32_e32 v18, v18
	v_exp_f32_e32 v19, v19
	s_nop 0
	v_pk_add_f32 v[18:19], v[18:19], 1.0 op_sel_hi:[1,0]
	s_nop 0
	v_rcp_f32_e32 v18, v18
	v_rcp_f32_e32 v19, v19
	s_nop 0
	v_pk_mul_f32 v[18:19], v[20:21], v[18:19]
	s_nop 0
	v_cvt_pk_bf16_f32 v29, v18, v19
	v_mad_i64_i32 v[18:19], s[2:3], v34, s14, v[132:133]
	global_store_dwordx4 v[18:19], v[26:29], off
	v_add_u32_e32 v18, 0xb0, v134
	v_ashrrev_i32_e32 v19, 31, v18
	v_lshl_add_u64 v[20:21], v[18:19], 2, s[46:47]
	s_waitcnt vmcnt(7)
	v_mov_b32_e32 v19, v184
	v_mul_f32_e32 v0, 0xbfb8aa3b, v19
	v_pk_mul_f32 v[22:23], v[10:11], v[0:1] op_sel_hi:[1,0]
	v_pk_mul_f32 v[12:13], v[12:13], v[0:1] op_sel_hi:[1,0]
	v_exp_f32_e32 v22, v22
	v_exp_f32_e32 v23, v23
	v_exp_f32_e32 v12, v12
	v_exp_f32_e32 v13, v13
	v_mul_f32_e32 v20, v19, v19
	v_pk_add_f32 v[22:23], v[22:23], 1.0 op_sel_hi:[1,0]
	v_pk_mul_f32 v[10:11], v[10:11], v[14:15]
	v_pk_add_f32 v[12:13], v[12:13], 1.0 op_sel_hi:[1,0]
	v_rcp_f32_e32 v22, v22
	v_rcp_f32_e32 v23, v23
	v_rcp_f32_e32 v12, v12
	v_rcp_f32_e32 v13, v13
	v_pk_mul_f32 v[10:11], v[10:11], v[20:21] op_sel_hi:[1,0]
	v_pk_mul_f32 v[14:15], v[16:17], v[20:21] op_sel_hi:[1,0]
	v_pk_mul_f32 v[10:11], v[10:11], v[22:23]
	v_pk_mul_f32 v[12:13], v[14:15], v[12:13]
	v_cvt_pk_bf16_f32 v10, v10, v11
	v_cvt_pk_bf16_f32 v11, v12, v13
	v_pk_mul_f32 v[12:13], v[2:3], v[0:1] op_sel_hi:[1,0]
	v_pk_mul_f32 v[2:3], v[2:3], v[6:7]
	v_exp_f32_e32 v12, v12
	v_exp_f32_e32 v13, v13
	v_pk_mul_f32 v[2:3], v[2:3], v[20:21] op_sel_hi:[1,0]
	v_pk_add_f32 v[12:13], v[12:13], 1.0 op_sel_hi:[1,0]
	s_nop 0
	v_rcp_f32_e32 v12, v12
	v_rcp_f32_e32 v13, v13
	s_nop 0
	v_pk_mul_f32 v[2:3], v[2:3], v[12:13]
	s_nop 0
	v_cvt_pk_bf16_f32 v12, v2, v3
	v_pk_mul_f32 v[2:3], v[4:5], v[0:1] op_sel_hi:[1,0]
	v_pk_mul_f32 v[4:5], v[8:9], v[20:21] op_sel_hi:[1,0]
	v_exp_f32_e32 v2, v2
	v_exp_f32_e32 v3, v3
	s_nop 0
	v_pk_add_f32 v[2:3], v[2:3], 1.0 op_sel_hi:[1,0]
	s_nop 0
	v_rcp_f32_e32 v2, v2
	v_rcp_f32_e32 v3, v3
	s_nop 0
	v_pk_mul_f32 v[2:3], v[4:5], v[2:3]
	s_nop 0
	v_cvt_pk_bf16_f32 v13, v2, v3
	v_mad_i64_i32 v[2:3], s[2:3], v18, s14, v[132:133]
	global_store_dwordx4 v[2:3], v[10:13], off
	s_cbranch_vccnz .LBB0_293

; __device__ __forceinline__ unsigned pack2(float a, float b) { f32v2_t v = {a, b}; bf16v2_t r = __builtin_convertvector(v, bf16v2_t); return __builtin_bit_cast(unsigned, r); }
; template <int EPI, int N, int K>
; __device__ __forceinline__ void gemm_phase(const KP& p, int l, const bfr* A, const bfr* Bt) {
;     ...
;         for (int m = 0; m < 4; ++m) {
;           int row = erow + ai * HM + wr * 64 + m * 16 + fr;
;           const float r = rs[row];
;           const float nrl = -1.44269504f * r, r2 = r * r;
;           u32x4 pk;
; #pragma unroll
;           for (int bj = 0; bj < 2; ++bj)
; #pragma unroll
;             for (int jj = 0; jj < 2; ++jj) {
;               f32v2_t g2 = {acc[ai][bj][m][0][2 * jj], acc[ai][bj][m][0][2 * jj + 1]};
;               f32v2_t u2 = {acc[ai][bj][m][1][2 * jj], acc[ai][bj][m][1][2 * jj + 1]};
;               f32v2_t t2 = g2 * nrl;
;               f32v2_t e2 = {__builtin_amdgcn_exp2f(t2.x), __builtin_amdgcn_exp2f(t2.y)};
;               f32v2_t d2 = e2 + 1.0f;
;               f32v2_t rc = {__builtin_amdgcn_rcpf(d2.x), __builtin_amdgcn_rcpf(d2.y)};
;               f32v2_t o2 = (g2 * u2) * r2 * rc;
;               pk[bj * 2 + jj] = pack2(o2.x, o2.y);
;             }
;           *(u32x4*)(act + (size_t)row * DFF + (ecol >> 1) + wc * 32 + fq * 8) = pk;
.LBB0_1141:
	v_add_u32_e32 v134, s46, v147
	v_ashrrev_i32_e32 v135, 31, v134
	v_lshl_add_u64 v[166:167], v[134:135], 2, s[0:1]
	global_load_dword v135, v[166:167], off
	global_load_dword v178, v[166:167], off offset:64
	global_load_dword v179, v[166:167], off offset:128
	global_load_dword v180, v[166:167], off offset:192
	global_load_dword v181, v[166:167], off offset:512
	global_load_dword v182, v[166:167], off offset:576
	global_load_dword v183, v[166:167], off offset:640
	global_load_dword v184, v[166:167], off offset:704
	v_pk_mul_f32 v[128:129], v[124:125], v[128:129]
	s_ashr_i32 s2, s50, 1
	v_pk_mul_f32 v[120:121], v[116:117], v[120:121]
	s_ashr_i32 s3, s2, 31
	v_lshl_add_u64 v[132:133], s[2:3], 1, v[130:131]
	s_movk_i32 s14, 0x1600
	v_pk_mul_f32 v[112:113], v[108:109], v[112:113]
	v_pk_mul_f32 v[104:105], v[100:101], v[104:105]
	v_pk_mul_f32 v[96:97], v[92:93], v[96:97]
	v_pk_mul_f32 v[88:89], v[84:85], v[88:89]
	v_pk_mul_f32 v[80:81], v[76:77], v[80:81]
	v_pk_mul_f32 v[72:73], v[68:69], v[72:73]
	v_pk_mul_f32 v[64:65], v[60:61], v[64:65]
	v_pk_mul_f32 v[56:57], v[52:53], v[56:57]
	v_pk_mul_f32 v[48:49], v[44:45], v[48:49]
	v_pk_mul_f32 v[40:41], v[36:37], v[40:41]
	v_pk_mul_f32 v[32:33], v[28:29], v[32:33]
	v_pk_mul_f32 v[24:25], v[20:21], v[24:25]
	v_pk_mul_f32 v[16:17], v[12:13], v[16:17]
	v_pk_mul_f32 v[8:9], v[4:5], v[8:9]
	s_andn2_b64 vcc, exec, s[42:43]
	s_mov_b32 s46, s44
	s_mov_b32 s50, s36
	s_waitcnt vmcnt(7)
	v_mul_f32_e32 v0, 0xbfb8aa3b, v135
	v_pk_mul_f32 v[168:169], v[122:123], v[0:1] op_sel_hi:[1,0]
	v_pk_mul_f32 v[124:125], v[124:125], v[0:1] op_sel_hi:[1,0]
	v_exp_f32_e32 v168, v168
	v_exp_f32_e32 v169, v169
	v_exp_f32_e32 v124, v124
	v_exp_f32_e32 v125, v125
	v_mul_f32_e32 v166, v135, v135
	v_pk_add_f32 v[168:169], v[168:169], 1.0 op_sel_hi:[1,0]
	v_pk_mul_f32 v[122:123], v[122:123], v[126:127]
	v_pk_add_f32 v[124:125], v[124:125], 1.0 op_sel_hi:[1,0]
	v_rcp_f32_e32 v168, v168
	v_rcp_f32_e32 v169, v169
	v_rcp_f32_e32 v124, v124
	v_rcp_f32_e32 v125, v125
	v_pk_mul_f32 v[122:123], v[122:123], v[166:167] op_sel_hi:[1,0]
	v_pk_mul_f32 v[126:127], v[128:129], v[166:167] op_sel_hi:[1,0]
	v_pk_mul_f32 v[122:123], v[122:123], v[168:169]
	v_pk_mul_f32 v[124:125], v[126:127], v[124:125]
	v_cvt_pk_bf16_f32 v122, v122, v123
	v_cvt_pk_bf16_f32 v123, v124, v125
	v_pk_mul_f32 v[124:125], v[114:115], v[0:1] op_sel_hi:[1,0]
	v_pk_mul_f32 v[114:115], v[114:115], v[118:119]
	v_exp_f32_e32 v124, v124
	v_exp_f32_e32 v125, v125
	v_pk_mul_f32 v[114:115], v[114:115], v[166:167] op_sel_hi:[1,0]
	v_pk_add_f32 v[124:125], v[124:125], 1.0 op_sel_hi:[1,0]
	s_nop 0
	v_rcp_f32_e32 v124, v124
	v_rcp_f32_e32 v125, v125
	s_nop 0
	v_pk_mul_f32 v[114:115], v[114:115], v[124:125]
	s_nop 0
	v_cvt_pk_bf16_f32 v124, v114, v115
	v_pk_mul_f32 v[114:115], v[116:117], v[0:1] op_sel_hi:[1,0]
	v_pk_mul_f32 v[116:117], v[120:121], v[166:167] op_sel_hi:[1,0]
	v_exp_f32_e32 v114, v114
	v_exp_f32_e32 v115, v115
	s_nop 0
	v_pk_add_f32 v[114:115], v[114:115], 1.0 op_sel_hi:[1,0]
	s_nop 0
	v_rcp_f32_e32 v114, v114
	v_rcp_f32_e32 v115, v115
	s_nop 0
	v_pk_mul_f32 v[114:115], v[116:117], v[114:115]
	s_nop 0
	v_cvt_pk_bf16_f32 v125, v114, v115
	v_mad_i64_i32 v[114:115], s[2:3], v134, s14, v[132:133]
	global_store_dwordx4 v[114:115], v[122:125], off
	v_or_b32_e32 v114, 16, v134
	v_ashrrev_i32_e32 v115, 31, v114
	v_lshl_add_u64 v[116:117], v[114:115], 2, s[0:1]
	s_waitcnt vmcnt(7)
	v_mov_b32_e32 v115, v178
	v_mul_f32_e32 v0, 0xbfb8aa3b, v115
	v_pk_mul_f32 v[118:119], v[106:107], v[0:1] op_sel_hi:[1,0]
	v_pk_mul_f32 v[108:109], v[108:109], v[0:1] op_sel_hi:[1,0]
	v_exp_f32_e32 v118, v118
	v_exp_f32_e32 v119, v119
	v_exp_f32_e32 v108, v108
	v_exp_f32_e32 v109, v109
	v_mul_f32_e32 v116, v115, v115
	v_pk_add_f32 v[118:119], v[118:119], 1.0 op_sel_hi:[1,0]
	v_pk_mul_f32 v[106:107], v[106:107], v[110:111]
	v_pk_add_f32 v[108:109], v[108:109], 1.0 op_sel_hi:[1,0]
	v_rcp_f32_e32 v118, v118
	v_rcp_f32_e32 v119, v119
	v_rcp_f32_e32 v108, v108
	v_rcp_f32_e32 v109, v109
	v_pk_mul_f32 v[106:107], v[106:107], v[116:117] op_sel_hi:[1,0]
	v_pk_mul_f32 v[110:111], v[112:113], v[116:117] op_sel_hi:[1,0]
	v_pk_mul_f32 v[106:107], v[106:107], v[118:119]
	v_pk_mul_f32 v[108:109], v[110:111], v[108:109]
	v_cvt_pk_bf16_f32 v106, v106, v107
	v_cvt_pk_bf16_f32 v107, v108, v109
	v_pk_mul_f32 v[108:109], v[98:99], v[0:1] op_sel_hi:[1,0]
	v_pk_mul_f32 v[98:99], v[98:99], v[102:103]
	v_exp_f32_e32 v108, v108
	v_exp_f32_e32 v109, v109
	v_pk_mul_f32 v[98:99], v[98:99], v[116:117] op_sel_hi:[1,0]
	v_pk_add_f32 v[108:109], v[108:109], 1.0 op_sel_hi:[1,0]
	s_nop 0
	v_rcp_f32_e32 v108, v108
	v_rcp_f32_e32 v109, v109
	s_nop 0
	v_pk_mul_f32 v[98:99], v[98:99], v[108:109]
	s_nop 0
	v_cvt_pk_bf16_f32 v108, v98, v99
	v_pk_mul_f32 v[98:99], v[100:101], v[0:1] op_sel_hi:[1,0]
	v_pk_mul_f32 v[100:101], v[104:105], v[116:117] op_sel_hi:[1,0]
	v_exp_f32_e32 v98, v98
	v_exp_f32_e32 v99, v99
	s_nop 0
	v_pk_add_f32 v[98:99], v[98:99], 1.0 op_sel_hi:[1,0]
	s_nop 0
	v_rcp_f32_e32 v98, v98
	v_rcp_f32_e32 v99, v99
	s_nop 0
	v_pk_mul_f32 v[98:99], v[100:101], v[98:99]
	s_nop 0
	v_cvt_pk_bf16_f32 v109, v98, v99
	v_mad_i64_i32 v[98:99], s[2:3], v114, s14, v[132:133]
	global_store_dwordx4 v[98:99], v[106:109], off
	v_or_b32_e32 v98, 32, v134
	v_ashrrev_i32_e32 v99, 31, v98
	v_lshl_add_u64 v[100:101], v[98:99], 2, s[0:1]
	s_waitcnt vmcnt(7)
; __device__ __forceinline__ unsigned pack2(float a, float b) { f32v2_t v = {a, b}; bf16v2_t r = __builtin_convertvector(v, bf16v2_t); return __builtin_bit_cast(unsigned, r); }
; template <int EPI, int N, int K>
; __device__ __forceinline__ void gemm_phase(const KP& p, int l, const bfr* A, const bfr* Bt) {
;     ...
;         for (int m = 0; m < 4; ++m) {
;           int row = erow + ai * HM + wr * 64 + m * 16 + fr;
;           const float r = rs[row];
;           const float nrl = -1.44269504f * r, r2 = r * r;
;           u32x4 pk;
; #pragma unroll
;           for (int bj = 0; bj < 2; ++bj)
; #pragma unroll
;             for (int jj = 0; jj < 2; ++jj) {
;               f32v2_t g2 = {acc[ai][bj][m][0][2 * jj], acc[ai][bj][m][0][2 * jj + 1]};
;               f32v2_t u2 = {acc[ai][bj][m][1][2 * jj], acc[ai][bj][m][1][2 * jj + 1]};
;               f32v2_t t2 = g2 * nrl;
;               f32v2_t e2 = {__builtin_amdgcn_exp2f(t2.x), __builtin_amdgcn_exp2f(t2.y)};
;               f32v2_t d2 = e2 + 1.0f;
;               f32v2_t rc = {__builtin_amdgcn_rcpf(d2.x), __builtin_amdgcn_rcpf(d2.y)};
;               f32v2_t o2 = (g2 * u2) * r2 * rc;
;               pk[bj * 2 + jj] = pack2(o2.x, o2.y);
;             }
;           *(u32x4*)(act + (size_t)row * DFF + (ecol >> 1) + wc * 32 + fq * 8) = pk;
	v_mov_b32_e32 v99, v179
	v_mul_f32_e32 v0, 0xbfb8aa3b, v99
	v_pk_mul_f32 v[102:103], v[90:91], v[0:1] op_sel_hi:[1,0]
	v_pk_mul_f32 v[92:93], v[92:93], v[0:1] op_sel_hi:[1,0]
	v_exp_f32_e32 v102, v102
	v_exp_f32_e32 v103, v103
	v_exp_f32_e32 v92, v92
	v_exp_f32_e32 v93, v93
	v_mul_f32_e32 v100, v99, v99
	v_pk_add_f32 v[102:103], v[102:103], 1.0 op_sel_hi:[1,0]
	v_pk_mul_f32 v[90:91], v[90:91], v[94:95]
	v_pk_add_f32 v[92:93], v[92:93], 1.0 op_sel_hi:[1,0]
	v_rcp_f32_e32 v102, v102
	v_rcp_f32_e32 v103, v103
	v_rcp_f32_e32 v92, v92
	v_rcp_f32_e32 v93, v93
	v_pk_mul_f32 v[90:91], v[90:91], v[100:101] op_sel_hi:[1,0]
	v_pk_mul_f32 v[94:95], v[96:97], v[100:101] op_sel_hi:[1,0]
	v_pk_mul_f32 v[90:91], v[90:91], v[102:103]
	v_pk_mul_f32 v[92:93], v[94:95], v[92:93]
	v_cvt_pk_bf16_f32 v90, v90, v91
	v_cvt_pk_bf16_f32 v91, v92, v93
	v_pk_mul_f32 v[92:93], v[82:83], v[0:1] op_sel_hi:[1,0]
	v_pk_mul_f32 v[82:83], v[82:83], v[86:87]
	v_exp_f32_e32 v92, v92
	v_exp_f32_e32 v93, v93
	v_pk_mul_f32 v[82:83], v[82:83], v[100:101] op_sel_hi:[1,0]
	v_pk_add_f32 v[92:93], v[92:93], 1.0 op_sel_hi:[1,0]
	s_nop 0
	v_rcp_f32_e32 v92, v92
	v_rcp_f32_e32 v93, v93
	s_nop 0
	v_pk_mul_f32 v[82:83], v[82:83], v[92:93]
	s_nop 0
	v_cvt_pk_bf16_f32 v92, v82, v83
	v_pk_mul_f32 v[82:83], v[84:85], v[0:1] op_sel_hi:[1,0]
	v_pk_mul_f32 v[84:85], v[88:89], v[100:101] op_sel_hi:[1,0]
	v_exp_f32_e32 v82, v82
	v_exp_f32_e32 v83, v83
	s_nop 0
	v_pk_add_f32 v[82:83], v[82:83], 1.0 op_sel_hi:[1,0]
	s_nop 0
	v_rcp_f32_e32 v82, v82
	v_rcp_f32_e32 v83, v83
	s_nop 0
	v_pk_mul_f32 v[82:83], v[84:85], v[82:83]
	s_nop 0
	v_cvt_pk_bf16_f32 v93, v82, v83
	v_mad_i64_i32 v[82:83], s[2:3], v98, s14, v[132:133]
	global_store_dwordx4 v[82:83], v[90:93], off
	v_or_b32_e32 v82, 48, v134
	v_ashrrev_i32_e32 v83, 31, v82
	v_lshl_add_u64 v[84:85], v[82:83], 2, s[0:1]
	s_waitcnt vmcnt(7)
	v_mov_b32_e32 v83, v180
	v_mul_f32_e32 v0, 0xbfb8aa3b, v83
	v_pk_mul_f32 v[86:87], v[74:75], v[0:1] op_sel_hi:[1,0]
	v_pk_mul_f32 v[76:77], v[76:77], v[0:1] op_sel_hi:[1,0]
	v_exp_f32_e32 v86, v86
	v_exp_f32_e32 v87, v87
	v_exp_f32_e32 v76, v76
	v_exp_f32_e32 v77, v77
	v_mul_f32_e32 v84, v83, v83
	v_pk_add_f32 v[86:87], v[86:87], 1.0 op_sel_hi:[1,0]
	v_pk_mul_f32 v[74:75], v[74:75], v[78:79]
	v_pk_add_f32 v[76:77], v[76:77], 1.0 op_sel_hi:[1,0]
	v_rcp_f32_e32 v86, v86
	v_rcp_f32_e32 v87, v87
	v_rcp_f32_e32 v76, v76
	v_rcp_f32_e32 v77, v77
	v_pk_mul_f32 v[74:75], v[74:75], v[84:85] op_sel_hi:[1,0]
	v_pk_mul_f32 v[78:79], v[80:81], v[84:85] op_sel_hi:[1,0]
	v_pk_mul_f32 v[74:75], v[74:75], v[86:87]
	v_pk_mul_f32 v[76:77], v[78:79], v[76:77]
	v_cvt_pk_bf16_f32 v74, v74, v75
	v_cvt_pk_bf16_f32 v75, v76, v77
	v_pk_mul_f32 v[76:77], v[66:67], v[0:1] op_sel_hi:[1,0]
	v_pk_mul_f32 v[66:67], v[66:67], v[70:71]
	v_exp_f32_e32 v76, v76
	v_exp_f32_e32 v77, v77
	v_pk_mul_f32 v[66:67], v[66:67], v[84:85] op_sel_hi:[1,0]
	v_pk_add_f32 v[76:77], v[76:77], 1.0 op_sel_hi:[1,0]
	s_nop 0
	v_rcp_f32_e32 v76, v76
	v_rcp_f32_e32 v77, v77
	s_nop 0
	v_pk_mul_f32 v[66:67], v[66:67], v[76:77]
	s_nop 0
	v_cvt_pk_bf16_f32 v76, v66, v67
	v_pk_mul_f32 v[66:67], v[68:69], v[0:1] op_sel_hi:[1,0]
	v_pk_mul_f32 v[68:69], v[72:73], v[84:85] op_sel_hi:[1,0]
	v_exp_f32_e32 v66, v66
	v_exp_f32_e32 v67, v67
	s_nop 0
	v_pk_add_f32 v[66:67], v[66:67], 1.0 op_sel_hi:[1,0]
	s_nop 0
	v_rcp_f32_e32 v66, v66
	v_rcp_f32_e32 v67, v67
	s_nop 0
	v_pk_mul_f32 v[66:67], v[68:69], v[66:67]
	s_nop 0
	v_cvt_pk_bf16_f32 v77, v66, v67
	v_mad_i64_i32 v[66:67], s[2:3], v82, s14, v[132:133]
	global_store_dwordx4 v[66:67], v[74:77], off
	v_add_u32_e32 v66, 0x80, v134
	v_ashrrev_i32_e32 v67, 31, v66
	v_lshl_add_u64 v[68:69], v[66:67], 2, s[0:1]
	s_waitcnt vmcnt(7)
	v_mov_b32_e32 v67, v181
	v_mul_f32_e32 v0, 0xbfb8aa3b, v67
	v_pk_mul_f32 v[70:71], v[58:59], v[0:1] op_sel_hi:[1,0]
	v_pk_mul_f32 v[60:61], v[60:61], v[0:1] op_sel_hi:[1,0]
	v_exp_f32_e32 v70, v70
	v_exp_f32_e32 v71, v71
	v_exp_f32_e32 v60, v60
	v_exp_f32_e32 v61, v61
	v_mul_f32_e32 v68, v67, v67
	v_pk_add_f32 v[70:71], v[70:71], 1.0 op_sel_hi:[1,0]
	v_pk_mul_f32 v[58:59], v[58:59], v[62:63]
	v_pk_add_f32 v[60:61], v[60:61], 1.0 op_sel_hi:[1,0]
	v_rcp_f32_e32 v70, v70
	v_rcp_f32_e32 v71, v71
	v_rcp_f32_e32 v60, v60
	v_rcp_f32_e32 v61, v61
	v_pk_mul_f32 v[58:59], v[58:59], v[68:69] op_sel_hi:[1,0]
	v_pk_mul_f32 v[62:63], v[64:65], v[68:69] op_sel_hi:[1,0]
	v_pk_mul_f32 v[58:59], v[58:59], v[70:71]
	v_pk_mul_f32 v[60:61], v[62:63], v[60:61]
	v_cvt_pk_bf16_f32 v58, v58, v59
	v_cvt_pk_bf16_f32 v59, v60, v61
	v_pk_mul_f32 v[60:61], v[50:51], v[0:1] op_sel_hi:[1,0]
	v_pk_mul_f32 v[50:51], v[50:51], v[54:55]
	v_exp_f32_e32 v60, v60
	v_exp_f32_e32 v61, v61
	v_pk_mul_f32 v[50:51], v[50:51], v[68:69] op_sel_hi:[1,0]
	v_pk_add_f32 v[60:61], v[60:61], 1.0 op_sel_hi:[1,0]
	s_nop 0
	v_rcp_f32_e32 v60, v60
	v_rcp_f32_e32 v61, v61
	s_nop 0
	v_pk_mul_f32 v[50:51], v[50:51], v[60:61]
	s_nop 0
	v_cvt_pk_bf16_f32 v60, v50, v51
	v_pk_mul_f32 v[50:51], v[52:53], v[0:1] op_sel_hi:[1,0]
	v_pk_mul_f32 v[52:53], v[56:57], v[68:69] op_sel_hi:[1,0]
	v_exp_f32_e32 v50, v50
	v_exp_f32_e32 v51, v51
	s_nop 0
	v_pk_add_f32 v[50:51], v[50:51], 1.0 op_sel_hi:[1,0]
	s_nop 0
	v_rcp_f32_e32 v50, v50
	v_rcp_f32_e32 v51, v51
	s_nop 0
	v_pk_mul_f32 v[50:51], v[52:53], v[50:51]
	s_nop 0
	v_cvt_pk_bf16_f32 v61, v50, v51
	v_mad_i64_i32 v[50:51], s[2:3], v66, s14, v[132:133]
	global_store_dwordx4 v[50:51], v[58:61], off
	v_add_u32_e32 v50, 0x90, v134
	v_ashrrev_i32_e32 v51, 31, v50
	v_lshl_add_u64 v[52:53], v[50:51], 2, s[0:1]
	s_waitcnt vmcnt(7)
; __device__ __forceinline__ unsigned pack2(float a, float b) { f32v2_t v = {a, b}; bf16v2_t r = __builtin_convertvector(v, bf16v2_t); return __builtin_bit_cast(unsigned, r); }
; template <int EPI, int N, int K>
; __device__ __forceinline__ void gemm_phase(const KP& p, int l, const bfr* A, const bfr* Bt) {
;     ...
;         for (int m = 0; m < 4; ++m) {
;           int row = erow + ai * HM + wr * 64 + m * 16 + fr;
;           const float r = rs[row];
;           const float nrl = -1.44269504f * r, r2 = r * r;
;           u32x4 pk;
; #pragma unroll
;           for (int bj = 0; bj < 2; ++bj)
; #pragma unroll
;             for (int jj = 0; jj < 2; ++jj) {
;               f32v2_t g2 = {acc[ai][bj][m][0][2 * jj], acc[ai][bj][m][0][2 * jj + 1]};
;               f32v2_t u2 = {acc[ai][bj][m][1][2 * jj], acc[ai][bj][m][1][2 * jj + 1]};
;               f32v2_t t2 = g2 * nrl;
;               f32v2_t e2 = {__builtin_amdgcn_exp2f(t2.x), __builtin_amdgcn_exp2f(t2.y)};
;               f32v2_t d2 = e2 + 1.0f;
;               f32v2_t rc = {__builtin_amdgcn_rcpf(d2.x), __builtin_amdgcn_rcpf(d2.y)};
;               f32v2_t o2 = (g2 * u2) * r2 * rc;
;               pk[bj * 2 + jj] = pack2(o2.x, o2.y);
;             }
;           *(u32x4*)(act + (size_t)row * DFF + (ecol >> 1) + wc * 32 + fq * 8) = pk;
	v_mov_b32_e32 v51, v182
	v_mul_f32_e32 v0, 0xbfb8aa3b, v51
	v_pk_mul_f32 v[54:55], v[42:43], v[0:1] op_sel_hi:[1,0]
	v_pk_mul_f32 v[44:45], v[44:45], v[0:1] op_sel_hi:[1,0]
	v_exp_f32_e32 v54, v54
	v_exp_f32_e32 v55, v55
	v_exp_f32_e32 v44, v44
	v_exp_f32_e32 v45, v45
	v_mul_f32_e32 v52, v51, v51
	v_pk_add_f32 v[54:55], v[54:55], 1.0 op_sel_hi:[1,0]
	v_pk_mul_f32 v[42:43], v[42:43], v[46:47]
	v_pk_add_f32 v[44:45], v[44:45], 1.0 op_sel_hi:[1,0]
	v_rcp_f32_e32 v54, v54
	v_rcp_f32_e32 v55, v55
	v_rcp_f32_e32 v44, v44
	v_rcp_f32_e32 v45, v45
	v_pk_mul_f32 v[42:43], v[42:43], v[52:53] op_sel_hi:[1,0]
	v_pk_mul_f32 v[46:47], v[48:49], v[52:53] op_sel_hi:[1,0]
	v_pk_mul_f32 v[42:43], v[42:43], v[54:55]
	v_pk_mul_f32 v[44:45], v[46:47], v[44:45]
	v_cvt_pk_bf16_f32 v42, v42, v43
	v_cvt_pk_bf16_f32 v43, v44, v45
	v_pk_mul_f32 v[44:45], v[34:35], v[0:1] op_sel_hi:[1,0]
	v_pk_mul_f32 v[34:35], v[34:35], v[38:39]
	v_exp_f32_e32 v44, v44
	v_exp_f32_e32 v45, v45
	v_pk_mul_f32 v[34:35], v[34:35], v[52:53] op_sel_hi:[1,0]
	v_pk_add_f32 v[44:45], v[44:45], 1.0 op_sel_hi:[1,0]
	s_nop 0
	v_rcp_f32_e32 v44, v44
	v_rcp_f32_e32 v45, v45
	s_nop 0
	v_pk_mul_f32 v[34:35], v[34:35], v[44:45]
	s_nop 0
	v_cvt_pk_bf16_f32 v44, v34, v35
	v_pk_mul_f32 v[34:35], v[36:37], v[0:1] op_sel_hi:[1,0]
	v_pk_mul_f32 v[36:37], v[40:41], v[52:53] op_sel_hi:[1,0]
	v_exp_f32_e32 v34, v34
	v_exp_f32_e32 v35, v35
	s_nop 0
	v_pk_add_f32 v[34:35], v[34:35], 1.0 op_sel_hi:[1,0]
	s_nop 0
	v_rcp_f32_e32 v34, v34
	v_rcp_f32_e32 v35, v35
	s_nop 0
	v_pk_mul_f32 v[34:35], v[36:37], v[34:35]
	s_nop 0
	v_cvt_pk_bf16_f32 v45, v34, v35
	v_mad_i64_i32 v[34:35], s[2:3], v50, s14, v[132:133]
	global_store_dwordx4 v[34:35], v[42:45], off
	v_add_u32_e32 v34, 0xa0, v134
	v_ashrrev_i32_e32 v35, 31, v34
	v_lshl_add_u64 v[36:37], v[34:35], 2, s[0:1]
	s_waitcnt vmcnt(7)
	v_mov_b32_e32 v35, v183
	v_mul_f32_e32 v0, 0xbfb8aa3b, v35
	v_pk_mul_f32 v[38:39], v[26:27], v[0:1] op_sel_hi:[1,0]
	v_pk_mul_f32 v[28:29], v[28:29], v[0:1] op_sel_hi:[1,0]
	v_exp_f32_e32 v38, v38
	v_exp_f32_e32 v39, v39
	v_exp_f32_e32 v28, v28
	v_exp_f32_e32 v29, v29
	v_mul_f32_e32 v36, v35, v35
	v_pk_add_f32 v[38:39], v[38:39], 1.0 op_sel_hi:[1,0]
	v_pk_mul_f32 v[26:27], v[26:27], v[30:31]
	v_pk_add_f32 v[28:29], v[28:29], 1.0 op_sel_hi:[1,0]
	v_rcp_f32_e32 v38, v38
	v_rcp_f32_e32 v39, v39
	v_rcp_f32_e32 v28, v28
	v_rcp_f32_e32 v29, v29
	v_pk_mul_f32 v[26:27], v[26:27], v[36:37] op_sel_hi:[1,0]
	v_pk_mul_f32 v[30:31], v[32:33], v[36:37] op_sel_hi:[1,0]
	v_pk_mul_f32 v[26:27], v[26:27], v[38:39]
	v_pk_mul_f32 v[28:29], v[30:31], v[28:29]
	v_cvt_pk_bf16_f32 v26, v26, v27
	v_cvt_pk_bf16_f32 v27, v28, v29
	v_pk_mul_f32 v[28:29], v[18:19], v[0:1] op_sel_hi:[1,0]
	v_pk_mul_f32 v[18:19], v[18:19], v[22:23]
	v_exp_f32_e32 v28, v28
	v_exp_f32_e32 v29, v29
	v_pk_mul_f32 v[18:19], v[18:19], v[36:37] op_sel_hi:[1,0]
	v_pk_add_f32 v[28:29], v[28:29], 1.0 op_sel_hi:[1,0]
	s_nop 0
	v_rcp_f32_e32 v28, v28
	v_rcp_f32_e32 v29, v29
	s_nop 0
	v_pk_mul_f32 v[18:19], v[18:19], v[28:29]
	s_nop 0
	v_cvt_pk_bf16_f32 v28, v18, v19
	v_pk_mul_f32 v[18:19], v[20:21], v[0:1] op_sel_hi:[1,0]
	v_pk_mul_f32 v[20:21], v[24:25], v[36:37] op_sel_hi:[1,0]
	v_exp_f32_e32 v18, v18
	v_exp_f32_e32 v19, v19
	s_nop 0
	v_pk_add_f32 v[18:19], v[18:19], 1.0 op_sel_hi:[1,0]
	s_nop 0
	v_rcp_f32_e32 v18, v18
	v_rcp_f32_e32 v19, v19
	s_nop 0
	v_pk_mul_f32 v[18:19], v[20:21], v[18:19]
	s_nop 0
	v_cvt_pk_bf16_f32 v29, v18, v19
	v_mad_i64_i32 v[18:19], s[2:3], v34, s14, v[132:133]
	global_store_dwordx4 v[18:19], v[26:29], off
	v_add_u32_e32 v18, 0xb0, v134
	v_ashrrev_i32_e32 v19, 31, v18
	v_lshl_add_u64 v[20:21], v[18:19], 2, s[0:1]
	s_waitcnt vmcnt(7)
	v_mov_b32_e32 v19, v184
	v_mul_f32_e32 v0, 0xbfb8aa3b, v19
	v_pk_mul_f32 v[22:23], v[10:11], v[0:1] op_sel_hi:[1,0]
	v_pk_mul_f32 v[12:13], v[12:13], v[0:1] op_sel_hi:[1,0]
	v_exp_f32_e32 v22, v22
	v_exp_f32_e32 v23, v23
	v_exp_f32_e32 v12, v12
	v_exp_f32_e32 v13, v13
	v_mul_f32_e32 v20, v19, v19
	v_pk_add_f32 v[22:23], v[22:23], 1.0 op_sel_hi:[1,0]
	v_pk_mul_f32 v[10:11], v[10:11], v[14:15]
	v_pk_add_f32 v[12:13], v[12:13], 1.0 op_sel_hi:[1,0]
	v_rcp_f32_e32 v22, v22
	v_rcp_f32_e32 v23, v23
	v_rcp_f32_e32 v12, v12
	v_rcp_f32_e32 v13, v13
	v_pk_mul_f32 v[10:11], v[10:11], v[20:21] op_sel_hi:[1,0]
	v_pk_mul_f32 v[14:15], v[16:17], v[20:21] op_sel_hi:[1,0]
	v_pk_mul_f32 v[10:11], v[10:11], v[22:23]
	v_pk_mul_f32 v[12:13], v[14:15], v[12:13]
	v_cvt_pk_bf16_f32 v10, v10, v11
	v_cvt_pk_bf16_f32 v11, v12, v13
	v_pk_mul_f32 v[12:13], v[2:3], v[0:1] op_sel_hi:[1,0]
	v_pk_mul_f32 v[2:3], v[2:3], v[6:7]
	v_exp_f32_e32 v12, v12
	v_exp_f32_e32 v13, v13
	v_pk_mul_f32 v[2:3], v[2:3], v[20:21] op_sel_hi:[1,0]
	v_pk_add_f32 v[12:13], v[12:13], 1.0 op_sel_hi:[1,0]
	s_nop 0
	v_rcp_f32_e32 v12, v12
	v_rcp_f32_e32 v13, v13
	s_nop 0
	v_pk_mul_f32 v[2:3], v[2:3], v[12:13]
	s_nop 0
	v_cvt_pk_bf16_f32 v12, v2, v3
	v_pk_mul_f32 v[2:3], v[4:5], v[0:1] op_sel_hi:[1,0]
	v_pk_mul_f32 v[4:5], v[8:9], v[20:21] op_sel_hi:[1,0]
	v_exp_f32_e32 v2, v2
	v_exp_f32_e32 v3, v3
	s_nop 0
	v_pk_add_f32 v[2:3], v[2:3], 1.0 op_sel_hi:[1,0]
	s_nop 0
	v_rcp_f32_e32 v2, v2
	v_rcp_f32_e32 v3, v3
	s_nop 0
	v_pk_mul_f32 v[2:3], v[4:5], v[2:3]
	s_nop 0
	v_cvt_pk_bf16_f32 v13, v2, v3
	v_mad_i64_i32 v[2:3], s[2:3], v18, s14, v[132:133]
	global_store_dwordx4 v[2:3], v[10:13], off
	s_cbranch_vccz .LBB0_1151
